# v15: grid barrier - XCD leaders arrive on the cross-XCD counter without a returning atomic and poll that counter against (gen+1)*nx, dropping the release-generation hop
# speedup vs baseline: 1.0251x; 1.0041x over previous
.LBB0_334:
	s_andn2_saveexec_b64 s[6:7], s[6:7]
	s_cbranch_execz .LBB0_352
	s_mov_b64 s[6:7], exec
	buffer_inv sc1
	buffer_wbl2 sc1
	v_add_u32_e32 v3, 1, v3
	v_mul_lo_u32 v3, v3, v2
	v_mov_b32_e32 v4, 0x1ac3000
	v_mov_b32_e32 v5, 1
	s_waitcnt vmcnt(0) lgkmcnt(0)
	global_atomic_add v4, v5, s[46:47] offset:1024
.Lxb_spin0:
	global_load_dword v2, v4, s[46:47] offset:1024 sc1
	s_waitcnt vmcnt(0)
	v_cmp_lt_u32_e32 vcc, v2, v3
	s_cbranch_vccz .Lxb_done0
	s_sleep 1
	s_branch .Lxb_spin0
.Lxb_done0:
	v_mov_b32_e32 v4, 0x2000
	global_atomic_add v4, v5, s[4:5] offset:1024

.LBB0_1453:
	s_andn2_saveexec_b64 s[10:11], s[10:11]
	s_cbranch_execz .LBB0_1471
	s_mov_b64 s[10:11], exec
	buffer_inv sc1
	buffer_wbl2 sc1
	v_add_u32_e32 v3, 1, v3
	v_mul_lo_u32 v3, v3, v2
	v_mov_b32_e32 v4, 0x1ac3000
	v_mov_b32_e32 v5, 1
	s_waitcnt vmcnt(0) lgkmcnt(0)
	global_atomic_add v4, v5, s[46:47] offset:1024

.LBB0_1737:
	s_andn2_saveexec_b64 s[8:9], s[8:9]
	s_cbranch_execz .LBB0_1755
	s_mov_b64 s[8:9], exec
	buffer_inv sc1
	buffer_wbl2 sc1
	v_add_u32_e32 v19, 1, v19
	v_mul_lo_u32 v19, v19, v18
	v_mov_b32_e32 v20, 0x1ac3000
	v_mov_b32_e32 v21, 1
	s_waitcnt vmcnt(0) lgkmcnt(0)
	global_atomic_add v20, v21, s[46:47] offset:1024
.Lxb_spin8:
	global_load_dword v18, v20, s[46:47] offset:1024 sc1
	s_waitcnt vmcnt(0)
	v_cmp_lt_u32_e32 vcc, v18, v19
	s_cbranch_vccz .Lxb_done8
	s_sleep 1
	s_branch .Lxb_spin8
.Lxb_done8:
	v_mov_b32_e32 v20, 0x2000
	global_atomic_add v20, v21, s[6:7] offset:1024

.LBB0_1821:
	s_andn2_saveexec_b64 s[6:7], s[6:7]
	s_cbranch_execz .LBB0_1839
	s_mov_b64 s[6:7], exec
	buffer_inv sc1
	buffer_wbl2 sc1
	v_add_u32_e32 v1, 1, v1
	v_mul_lo_u32 v1, v1, v0
	v_mov_b32_e32 v2, 0x1ac3000
	v_mov_b32_e32 v3, 1
	s_waitcnt vmcnt(0) lgkmcnt(0)
	global_atomic_add v2, v3, s[46:47] offset:1024
.Lxb_spin9:
	global_load_dword v0, v2, s[46:47] offset:1024 sc1
	s_waitcnt vmcnt(0)
	v_cmp_lt_u32_e32 vcc, v0, v1
	s_cbranch_vccz .Lxb_done9
	s_sleep 1
	s_branch .Lxb_spin9
.Lxb_done9:
	v_mov_b32_e32 v2, 0x2000
	global_atomic_add v2, v3, s[4:5] offset:1024
